# c10 + GDN stage 3/4 rewritten: wave-specialised straight-line 16x16 KK/QK tiles (immediates, counted waits) and diagonal-block inverse as right-looking substitution from a transposed f32 image (stream
# speedup vs baseline: 1.0127x; 1.0087x over previous
.Lgpf_skip:
	v_lshrrev_b32_e32 v207, 4, v3
	v_mul_u32_u24_e32 v116, 0x110, v206
	v_mul_u32_u24_e32 v115, 0x90, v206
	s_mov_b32 s27, 0x1a400
	v_lshlrev_b32_e32 v208, 3, v207
	v_lshlrev_b32_e32 v209, 3, v207
	v_lshl_add_u32 v116, v207, 4, v116
	v_lshl_add_u32 v117, v206, 2, s81
	v_lshl_add_u32 v114, v207, 4, s81
	v_add3_u32 v115, v115, v208, s27
	v_or_b32_e32 v118, s84, v206
	v_lshlrev_b32_e32 v119, 2, v207
	v_mul_u32_u24_e32 v136, 0x140, v207
	v_sub_u32_e32 v119, v206, v119
	v_lshl_add_u32 v136, v206, 2, v136
	v_add_u32_e32 v136, s97, v136
	s_cmp_lt_u32 s79, 4
	s_cbranch_scc1 .Lgt_lo
	s_cmp_lt_u32 s79, 6
	s_cbranch_scc1 .Lgt_45
	s_cmp_eq_u32 s79, 6
	s_cbranch_scc1 .Lgt_w6
	ds_read_b128 v[120:123], v116 offset:21760
	ds_read_b128 v[142:145], v116 offset:13056
	ds_read_b128 v[124:127], v116 offset:21824
	ds_read_b128 v[146:149], v116 offset:13120
	ds_read_b128 v[128:131], v116 offset:21888
	ds_read_b128 v[150:153], v116 offset:13184
	ds_read_b128 v[132:135], v116 offset:21952
	ds_read_b128 v[154:157], v116 offset:13248
	ds_read_b32 v112, v117 offset:192
	ds_read_b128 v[160:163], v114 offset:64
	s_waitcnt lgkmcnt(8)
	v_mfma_f32_16x16x32_bf16 v[108:111], v[120:123], v[142:145], 0
	s_waitcnt lgkmcnt(6)
	v_mfma_f32_16x16x32_bf16 v[108:111], v[124:127], v[146:149], v[108:111]
	s_waitcnt lgkmcnt(4)
	v_mfma_f32_16x16x32_bf16 v[108:111], v[128:131], v[150:153], v[108:111]
	s_waitcnt lgkmcnt(2)
	v_mfma_f32_16x16x32_bf16 v[108:111], v[132:135], v[154:157], v[108:111]
	s_waitcnt lgkmcnt(0)
	v_sub_f32_e32 v164, v112, v160
	v_sub_f32_e32 v165, v112, v161
	v_sub_f32_e32 v166, v112, v162
	v_sub_f32_e32 v167, v112, v163
	v_mul_f32_e32 v164, 0x3fb8aa3b, v164
	v_mul_f32_e32 v165, 0x3fb8aa3b, v165
	v_mul_f32_e32 v166, 0x3fb8aa3b, v166
	v_mul_f32_e32 v167, 0x3fb8aa3b, v167
	v_exp_f32_e32 v164, v164
	v_exp_f32_e32 v165, v165
	v_exp_f32_e32 v166, v166
	v_exp_f32_e32 v167, v167
	v_mul_f32_e32 v108, v108, v164
	v_mul_f32_e32 v109, v109, v165
	v_mul_f32_e32 v110, v110, v166
	v_mul_f32_e32 v111, v111, v167
	v_cvt_pk_bf16_f32 v168, v108, v109
	v_cvt_pk_bf16_f32 v169, v110, v111
	ds_write_b64 v115, v[168:169] offset:6944
	ds_read_b128 v[120:123], v116 offset:26112
	ds_read_b128 v[142:145], v116 offset:13056
	ds_read_b128 v[124:127], v116 offset:26176
	ds_read_b128 v[146:149], v116 offset:13120
	ds_read_b128 v[128:131], v116 offset:26240
	ds_read_b128 v[150:153], v116 offset:13184
	ds_read_b128 v[132:135], v116 offset:26304
	ds_read_b128 v[154:157], v116 offset:13248
	ds_read_b32 v112, v117 offset:192
	ds_read_b128 v[160:163], v114 offset:128
	s_waitcnt lgkmcnt(8)
	v_mfma_f32_16x16x32_bf16 v[108:111], v[120:123], v[142:145], 0
	s_waitcnt lgkmcnt(6)
	v_mfma_f32_16x16x32_bf16 v[108:111], v[124:127], v[146:149], v[108:111]
	s_waitcnt lgkmcnt(4)
	v_mfma_f32_16x16x32_bf16 v[108:111], v[128:131], v[150:153], v[108:111]
	s_waitcnt lgkmcnt(2)
	v_mfma_f32_16x16x32_bf16 v[108:111], v[132:135], v[154:157], v[108:111]
	s_waitcnt lgkmcnt(0)
	v_sub_f32_e32 v164, v112, v160
	v_sub_f32_e32 v165, v112, v161
	v_sub_f32_e32 v166, v112, v162
	v_sub_f32_e32 v167, v112, v163
	v_mul_f32_e32 v164, 0x3fb8aa3b, v164
	v_mul_f32_e32 v165, 0x3fb8aa3b, v165
	v_mul_f32_e32 v166, 0x3fb8aa3b, v166
	v_mul_f32_e32 v167, 0x3fb8aa3b, v167
	v_exp_f32_e32 v164, v164
	v_exp_f32_e32 v165, v165
	v_exp_f32_e32 v166, v166
	v_exp_f32_e32 v167, v167
	v_mul_f32_e32 v108, v108, v164
	v_mul_f32_e32 v109, v109, v165
	v_mul_f32_e32 v110, v110, v166
	v_mul_f32_e32 v111, v111, v167
	v_cvt_pk_bf16_f32 v168, v108, v109
	v_cvt_pk_bf16_f32 v169, v110, v111
	ds_write_b64 v115, v[168:169] offset:6976
	ds_read_b128 v[120:123], v116 offset:30464
	ds_read_b128 v[142:145], v116 offset:13056
	ds_read_b128 v[124:127], v116 offset:30528
	ds_read_b128 v[146:149], v116 offset:13120
	ds_read_b128 v[128:131], v116 offset:30592
	ds_read_b128 v[150:153], v116 offset:13184
	ds_read_b128 v[132:135], v116 offset:30656
	ds_read_b128 v[154:157], v116 offset:13248
	ds_read_b32 v112, v117 offset:192
	ds_read_b128 v[160:163], v114 offset:192
	v_cmp_le_i32_e64 s[10:11], 0, v119
	v_cmp_le_i32_e64 s[12:13], 1, v119
	v_cmp_le_i32_e64 s[48:49], 2, v119
	v_cmp_le_i32_e64 s[50:51], 3, v119
	s_waitcnt lgkmcnt(8)
	v_mfma_f32_16x16x32_bf16 v[108:111], v[120:123], v[142:145], 0
	s_waitcnt lgkmcnt(6)
	v_mfma_f32_16x16x32_bf16 v[108:111], v[124:127], v[146:149], v[108:111]
	s_waitcnt lgkmcnt(4)
	v_mfma_f32_16x16x32_bf16 v[108:111], v[128:131], v[150:153], v[108:111]
	s_waitcnt lgkmcnt(2)
	v_mfma_f32_16x16x32_bf16 v[108:111], v[132:135], v[154:157], v[108:111]
	s_waitcnt lgkmcnt(0)
	v_sub_f32_e32 v164, v112, v160
	v_sub_f32_e32 v165, v112, v161
	v_sub_f32_e32 v166, v112, v162
	v_sub_f32_e32 v167, v112, v163
	v_mul_f32_e32 v164, 0x3fb8aa3b, v164
	v_mul_f32_e32 v165, 0x3fb8aa3b, v165
	v_mul_f32_e32 v166, 0x3fb8aa3b, v166
	v_mul_f32_e32 v167, 0x3fb8aa3b, v167
	v_exp_f32_e32 v164, v164
	v_exp_f32_e32 v165, v165
	v_exp_f32_e32 v166, v166
	v_exp_f32_e32 v167, v167
	v_mul_f32_e32 v108, v108, v164
	v_mul_f32_e32 v109, v109, v165
	v_mul_f32_e32 v110, v110, v166
	v_mul_f32_e32 v111, v111, v167
	v_cndmask_b32_e64 v108, 0, v108, s[10:11]
	v_cndmask_b32_e64 v109, 0, v109, s[12:13]
	v_cndmask_b32_e64 v110, 0, v110, s[48:49]
	v_cndmask_b32_e64 v111, 0, v111, s[50:51]
	v_cvt_pk_bf16_f32 v168, v108, v109
	v_cvt_pk_bf16_f32 v169, v110, v111
	ds_write_b64 v115, v[168:169] offset:7008
	s_branch .Lgt_end
.Lgt_w6:
	ds_read_b128 v[120:123], v116 offset:21760
	ds_read_b128 v[142:145], v116 offset:8704
	ds_read_b128 v[124:127], v116 offset:21824
	ds_read_b128 v[146:149], v116 offset:8768
	ds_read_b128 v[128:131], v116 offset:21888
	ds_read_b128 v[150:153], v116 offset:8832
	ds_read_b128 v[132:135], v116 offset:21952
	ds_read_b128 v[154:157], v116 offset:8896
	ds_read_b32 v112, v117 offset:128
	ds_read_b128 v[160:163], v114 offset:64
	s_waitcnt lgkmcnt(8)
	v_mfma_f32_16x16x32_bf16 v[108:111], v[120:123], v[142:145], 0
	s_waitcnt lgkmcnt(6)
	v_mfma_f32_16x16x32_bf16 v[108:111], v[124:127], v[146:149], v[108:111]
	s_waitcnt lgkmcnt(4)
	v_mfma_f32_16x16x32_bf16 v[108:111], v[128:131], v[150:153], v[108:111]
	s_waitcnt lgkmcnt(2)
	v_mfma_f32_16x16x32_bf16 v[108:111], v[132:135], v[154:157], v[108:111]
	s_waitcnt lgkmcnt(0)
	v_sub_f32_e32 v164, v112, v160
	v_sub_f32_e32 v165, v112, v161
	v_sub_f32_e32 v166, v112, v162
	v_sub_f32_e32 v167, v112, v163
	v_mul_f32_e32 v164, 0x3fb8aa3b, v164
	v_mul_f32_e32 v165, 0x3fb8aa3b, v165
	v_mul_f32_e32 v166, 0x3fb8aa3b, v166
	v_mul_f32_e32 v167, 0x3fb8aa3b, v167
	v_exp_f32_e32 v164, v164
	v_exp_f32_e32 v165, v165
	v_exp_f32_e32 v166, v166
	v_exp_f32_e32 v167, v167
	v_mul_f32_e32 v108, v108, v164
	v_mul_f32_e32 v109, v109, v165
	v_mul_f32_e32 v110, v110, v166
	v_mul_f32_e32 v111, v111, v167
	v_cvt_pk_bf16_f32 v168, v108, v109
	v_cvt_pk_bf16_f32 v169, v110, v111
	ds_write_b64 v115, v[168:169] offset:4640
	ds_read_b128 v[120:123], v116 offset:26112
	ds_read_b128 v[142:145], v116 offset:8704
	ds_read_b128 v[124:127], v116 offset:26176
	ds_read_b128 v[146:149], v116 offset:8768
	ds_read_b128 v[128:131], v116 offset:26240
	ds_read_b128 v[150:153], v116 offset:8832
	ds_read_b128 v[132:135], v116 offset:26304
	ds_read_b128 v[154:157], v116 offset:8896
	ds_read_b32 v112, v117 offset:128
	ds_read_b128 v[160:163], v114 offset:128
	v_cmp_le_i32_e64 s[10:11], 0, v119
	v_cmp_le_i32_e64 s[12:13], 1, v119
	v_cmp_le_i32_e64 s[48:49], 2, v119
	v_cmp_le_i32_e64 s[50:51], 3, v119
	s_waitcnt lgkmcnt(8)
	v_mfma_f32_16x16x32_bf16 v[108:111], v[120:123], v[142:145], 0
	s_waitcnt lgkmcnt(6)
	v_mfma_f32_16x16x32_bf16 v[108:111], v[124:127], v[146:149], v[108:111]
	s_waitcnt lgkmcnt(4)
	v_mfma_f32_16x16x32_bf16 v[108:111], v[128:131], v[150:153], v[108:111]
	s_waitcnt lgkmcnt(2)
	v_mfma_f32_16x16x32_bf16 v[108:111], v[132:135], v[154:157], v[108:111]
	s_waitcnt lgkmcnt(0)
	v_sub_f32_e32 v164, v112, v160
	v_sub_f32_e32 v165, v112, v161
	v_sub_f32_e32 v166, v112, v162
	v_sub_f32_e32 v167, v112, v163
	v_mul_f32_e32 v164, 0x3fb8aa3b, v164
	v_mul_f32_e32 v165, 0x3fb8aa3b, v165
	v_mul_f32_e32 v166, 0x3fb8aa3b, v166
	v_mul_f32_e32 v167, 0x3fb8aa3b, v167
	v_exp_f32_e32 v164, v164
	v_exp_f32_e32 v165, v165
	v_exp_f32_e32 v166, v166
	v_exp_f32_e32 v167, v167
	v_mul_f32_e32 v108, v108, v164
	v_mul_f32_e32 v109, v109, v165
	v_mul_f32_e32 v110, v110, v166
	v_mul_f32_e32 v111, v111, v167
	v_cndmask_b32_e64 v108, 0, v108, s[10:11]
	v_cndmask_b32_e64 v109, 0, v109, s[12:13]
	v_cndmask_b32_e64 v110, 0, v110, s[48:49]
	v_cndmask_b32_e64 v111, 0, v111, s[50:51]
	v_cvt_pk_bf16_f32 v168, v108, v109
	v_cvt_pk_bf16_f32 v169, v110, v111
	ds_write_b64 v115, v[168:169] offset:4672
	ds_read_b128 v[120:123], v116 offset:17408
	ds_read_b128 v[142:145], v116 offset:13056
	ds_read_b128 v[124:127], v116 offset:17472
	ds_read_b128 v[146:149], v116 offset:13120
	ds_read_b128 v[128:131], v116 offset:17536
	ds_read_b128 v[150:153], v116 offset:13184
	ds_read_b128 v[132:135], v116 offset:17600
	ds_read_b128 v[154:157], v116 offset:13248
	ds_read_b32 v112, v117 offset:192
	ds_read_b128 v[160:163], v114 offset:0
	s_waitcnt lgkmcnt(8)
	v_mfma_f32_16x16x32_bf16 v[108:111], v[120:123], v[142:145], 0
	s_waitcnt lgkmcnt(6)
	v_mfma_f32_16x16x32_bf16 v[108:111], v[124:127], v[146:149], v[108:111]
	s_waitcnt lgkmcnt(4)
	v_mfma_f32_16x16x32_bf16 v[108:111], v[128:131], v[150:153], v[108:111]
	s_waitcnt lgkmcnt(2)
	v_mfma_f32_16x16x32_bf16 v[108:111], v[132:135], v[154:157], v[108:111]
	s_waitcnt lgkmcnt(0)
	v_sub_f32_e32 v164, v112, v160
	v_sub_f32_e32 v165, v112, v161
	v_sub_f32_e32 v166, v112, v162
	v_sub_f32_e32 v167, v112, v163
	v_mul_f32_e32 v164, 0x3fb8aa3b, v164
	v_mul_f32_e32 v165, 0x3fb8aa3b, v165
	v_mul_f32_e32 v166, 0x3fb8aa3b, v166
	v_mul_f32_e32 v167, 0x3fb8aa3b, v167
	v_exp_f32_e32 v164, v164
	v_exp_f32_e32 v165, v165
	v_exp_f32_e32 v166, v166
	v_exp_f32_e32 v167, v167
	v_mul_f32_e32 v108, v108, v164
	v_mul_f32_e32 v109, v109, v165
	v_mul_f32_e32 v110, v110, v166
	v_mul_f32_e32 v111, v111, v167
	v_cvt_pk_bf16_f32 v168, v108, v109
	v_cvt_pk_bf16_f32 v169, v110, v111
	ds_write_b64 v115, v[168:169] offset:6912
	s_branch .Lgt_end
.Lgt_45:
	s_cmp_eq_u32 s79, 4
	s_cbranch_scc1 .Lgt_w4
	ds_read_b128 v[120:123], v116 offset:17408
	ds_read_b128 v[142:145], v116 offset:4352
	ds_read_b128 v[124:127], v116 offset:17472
	ds_read_b128 v[146:149], v116 offset:4416
	ds_read_b128 v[128:131], v116 offset:17536
	ds_read_b128 v[150:153], v116 offset:4480
	ds_read_b128 v[132:135], v116 offset:17600
	ds_read_b128 v[154:157], v116 offset:4544
	ds_read_b32 v112, v117 offset:64
	ds_read_b128 v[160:163], v114 offset:0
	s_waitcnt lgkmcnt(8)
	v_mfma_f32_16x16x32_bf16 v[108:111], v[120:123], v[142:145], 0
	s_waitcnt lgkmcnt(6)
	v_mfma_f32_16x16x32_bf16 v[108:111], v[124:127], v[146:149], v[108:111]
	s_waitcnt lgkmcnt(4)
	v_mfma_f32_16x16x32_bf16 v[108:111], v[128:131], v[150:153], v[108:111]
	s_waitcnt lgkmcnt(2)
	v_mfma_f32_16x16x32_bf16 v[108:111], v[132:135], v[154:157], v[108:111]
	s_waitcnt lgkmcnt(0)
	v_sub_f32_e32 v164, v112, v160
	v_sub_f32_e32 v165, v112, v161
	v_sub_f32_e32 v166, v112, v162
	v_sub_f32_e32 v167, v112, v163
	v_mul_f32_e32 v164, 0x3fb8aa3b, v164
	v_mul_f32_e32 v165, 0x3fb8aa3b, v165
	v_mul_f32_e32 v166, 0x3fb8aa3b, v166
	v_mul_f32_e32 v167, 0x3fb8aa3b, v167
	v_exp_f32_e32 v164, v164
	v_exp_f32_e32 v165, v165
	v_exp_f32_e32 v166, v166
	v_exp_f32_e32 v167, v167
	v_mul_f32_e32 v108, v108, v164
	v_mul_f32_e32 v109, v109, v165
	v_mul_f32_e32 v110, v110, v166
	v_mul_f32_e32 v111, v111, v167
	v_cvt_pk_bf16_f32 v168, v108, v109
	v_cvt_pk_bf16_f32 v169, v110, v111
	ds_write_b64 v115, v[168:169] offset:2304
	ds_read_b128 v[120:123], v116 offset:21760
	ds_read_b128 v[142:145], v116 offset:4352
	ds_read_b128 v[124:127], v116 offset:21824
	ds_read_b128 v[146:149], v116 offset:4416
	ds_read_b128 v[128:131], v116 offset:21888
	ds_read_b128 v[150:153], v116 offset:4480
	ds_read_b128 v[132:135], v116 offset:21952
	ds_read_b128 v[154:157], v116 offset:4544
	ds_read_b32 v112, v117 offset:64
	ds_read_b128 v[160:163], v114 offset:64
	v_cmp_le_i32_e64 s[10:11], 0, v119
	v_cmp_le_i32_e64 s[12:13], 1, v119
	v_cmp_le_i32_e64 s[48:49], 2, v119
	v_cmp_le_i32_e64 s[50:51], 3, v119
	s_waitcnt lgkmcnt(8)
	v_mfma_f32_16x16x32_bf16 v[108:111], v[120:123], v[142:145], 0
	s_waitcnt lgkmcnt(6)
	v_mfma_f32_16x16x32_bf16 v[108:111], v[124:127], v[146:149], v[108:111]
	s_waitcnt lgkmcnt(4)
	v_mfma_f32_16x16x32_bf16 v[108:111], v[128:131], v[150:153], v[108:111]
	s_waitcnt lgkmcnt(2)
	v_mfma_f32_16x16x32_bf16 v[108:111], v[132:135], v[154:157], v[108:111]
	s_waitcnt lgkmcnt(0)
	v_sub_f32_e32 v164, v112, v160
	v_sub_f32_e32 v165, v112, v161
	v_sub_f32_e32 v166, v112, v162
	v_sub_f32_e32 v167, v112, v163
	v_mul_f32_e32 v164, 0x3fb8aa3b, v164
	v_mul_f32_e32 v165, 0x3fb8aa3b, v165
	v_mul_f32_e32 v166, 0x3fb8aa3b, v166
	v_mul_f32_e32 v167, 0x3fb8aa3b, v167
	v_exp_f32_e32 v164, v164
	v_exp_f32_e32 v165, v165
	v_exp_f32_e32 v166, v166
	v_exp_f32_e32 v167, v167
	v_mul_f32_e32 v108, v108, v164
	v_mul_f32_e32 v109, v109, v165
	v_mul_f32_e32 v110, v110, v166
	v_mul_f32_e32 v111, v111, v167
	v_cndmask_b32_e64 v108, 0, v108, s[10:11]
	v_cndmask_b32_e64 v109, 0, v109, s[12:13]
	v_cndmask_b32_e64 v110, 0, v110, s[48:49]
	v_cndmask_b32_e64 v111, 0, v111, s[50:51]
	v_cvt_pk_bf16_f32 v168, v108, v109
	v_cvt_pk_bf16_f32 v169, v110, v111
	ds_write_b64 v115, v[168:169] offset:2336
	ds_read_b128 v[120:123], v116 offset:17408
	ds_read_b128 v[142:145], v116 offset:8704
	ds_read_b128 v[124:127], v116 offset:17472
	ds_read_b128 v[146:149], v116 offset:8768
	ds_read_b128 v[128:131], v116 offset:17536
	ds_read_b128 v[150:153], v116 offset:8832
	ds_read_b128 v[132:135], v116 offset:17600
	ds_read_b128 v[154:157], v116 offset:8896
	ds_read_b32 v112, v117 offset:128
	ds_read_b128 v[160:163], v114 offset:0
	s_waitcnt lgkmcnt(8)
	v_mfma_f32_16x16x32_bf16 v[108:111], v[120:123], v[142:145], 0
	s_waitcnt lgkmcnt(6)
	v_mfma_f32_16x16x32_bf16 v[108:111], v[124:127], v[146:149], v[108:111]
	s_waitcnt lgkmcnt(4)
	v_mfma_f32_16x16x32_bf16 v[108:111], v[128:131], v[150:153], v[108:111]
	s_waitcnt lgkmcnt(2)
	v_mfma_f32_16x16x32_bf16 v[108:111], v[132:135], v[154:157], v[108:111]
	s_waitcnt lgkmcnt(0)
	v_sub_f32_e32 v164, v112, v160
	v_sub_f32_e32 v165, v112, v161
	v_sub_f32_e32 v166, v112, v162
	v_sub_f32_e32 v167, v112, v163
	v_mul_f32_e32 v164, 0x3fb8aa3b, v164
	v_mul_f32_e32 v165, 0x3fb8aa3b, v165
	v_mul_f32_e32 v166, 0x3fb8aa3b, v166
	v_mul_f32_e32 v167, 0x3fb8aa3b, v167
	v_exp_f32_e32 v164, v164
	v_exp_f32_e32 v165, v165
	v_exp_f32_e32 v166, v166
	v_exp_f32_e32 v167, v167
	v_mul_f32_e32 v108, v108, v164
	v_mul_f32_e32 v109, v109, v165
	v_mul_f32_e32 v110, v110, v166
	v_mul_f32_e32 v111, v111, v167
	v_cvt_pk_bf16_f32 v168, v108, v109
	v_cvt_pk_bf16_f32 v169, v110, v111
	ds_write_b64 v115, v[168:169] offset:4608
	s_branch .Lgt_end
.Lgt_w4:
	ds_read_b128 v[120:123], v116 offset:21760
	ds_read_b128 v[142:145], v116 offset:30464
	ds_read_b128 v[124:127], v116 offset:21824
	ds_read_b128 v[146:149], v116 offset:30528
	ds_read_b128 v[128:131], v116 offset:21888
	ds_read_b128 v[150:153], v116 offset:30592
	ds_read_b128 v[132:135], v116 offset:21952
	ds_read_b128 v[154:157], v116 offset:30656
	ds_read_b32 v112, v117 offset:192
	ds_read_b32 v113, v117 offset:2240
	ds_read_b128 v[160:163], v114 offset:64
	s_waitcnt lgkmcnt(9)
	v_mfma_f32_16x16x32_bf16 v[108:111], v[120:123], v[142:145], 0
	s_waitcnt lgkmcnt(7)
	v_mfma_f32_16x16x32_bf16 v[108:111], v[124:127], v[146:149], v[108:111]
	s_waitcnt lgkmcnt(5)
	v_mfma_f32_16x16x32_bf16 v[108:111], v[128:131], v[150:153], v[108:111]
	s_waitcnt lgkmcnt(3)
	v_mfma_f32_16x16x32_bf16 v[108:111], v[132:135], v[154:157], v[108:111]
	s_waitcnt lgkmcnt(0)
	v_sub_f32_e32 v164, v112, v160
	v_sub_f32_e32 v165, v112, v161
	v_sub_f32_e32 v166, v112, v162
	v_sub_f32_e32 v167, v112, v163
	v_mul_f32_e32 v164, 0x3fb8aa3b, v164
	v_mul_f32_e32 v165, 0x3fb8aa3b, v165
	v_mul_f32_e32 v166, 0x3fb8aa3b, v166
	v_mul_f32_e32 v167, 0x3fb8aa3b, v167
	v_exp_f32_e32 v164, v164
	v_exp_f32_e32 v165, v165
	v_exp_f32_e32 v166, v166
	v_exp_f32_e32 v167, v167
	v_mul_f32_e32 v108, v108, v113
	v_mul_f32_e32 v109, v109, v113
	v_mul_f32_e32 v110, v110, v113
	v_mul_f32_e32 v111, v111, v113
	v_mul_f32_e32 v108, v108, v164
	v_mul_f32_e32 v109, v109, v165
	v_mul_f32_e32 v110, v110, v166
	v_mul_f32_e32 v111, v111, v167
	v_cvt_pk_bf16_f32 v168, -v108, -v109
	v_cvt_pk_bf16_f32 v169, -v110, -v111
	ds_write_b64 v115, v[168:169] offset:23840
	ds_read_b128 v[120:123], v116 offset:26112
	ds_read_b128 v[142:145], v116 offset:30464
	ds_read_b128 v[124:127], v116 offset:26176
	ds_read_b128 v[146:149], v116 offset:30528
	ds_read_b128 v[128:131], v116 offset:26240
	ds_read_b128 v[150:153], v116 offset:30592
	ds_read_b128 v[132:135], v116 offset:26304
	ds_read_b128 v[154:157], v116 offset:30656
	ds_read_b32 v112, v117 offset:192
	ds_read_b32 v113, v117 offset:2240
	ds_read_b128 v[160:163], v114 offset:128
	s_waitcnt lgkmcnt(9)
	v_mfma_f32_16x16x32_bf16 v[108:111], v[120:123], v[142:145], 0
	s_waitcnt lgkmcnt(7)
	v_mfma_f32_16x16x32_bf16 v[108:111], v[124:127], v[146:149], v[108:111]
	s_waitcnt lgkmcnt(5)
	v_mfma_f32_16x16x32_bf16 v[108:111], v[128:131], v[150:153], v[108:111]
	s_waitcnt lgkmcnt(3)
	v_mfma_f32_16x16x32_bf16 v[108:111], v[132:135], v[154:157], v[108:111]
	s_waitcnt lgkmcnt(0)
	v_sub_f32_e32 v164, v112, v160
	v_sub_f32_e32 v165, v112, v161
	v_sub_f32_e32 v166, v112, v162
	v_sub_f32_e32 v167, v112, v163
	v_mul_f32_e32 v164, 0x3fb8aa3b, v164
	v_mul_f32_e32 v165, 0x3fb8aa3b, v165
	v_mul_f32_e32 v166, 0x3fb8aa3b, v166
	v_mul_f32_e32 v167, 0x3fb8aa3b, v167
	v_exp_f32_e32 v164, v164
	v_exp_f32_e32 v165, v165
	v_exp_f32_e32 v166, v166
	v_exp_f32_e32 v167, v167
	v_mul_f32_e32 v108, v108, v113
	v_mul_f32_e32 v109, v109, v113
	v_mul_f32_e32 v110, v110, v113
	v_mul_f32_e32 v111, v111, v113
	v_mul_f32_e32 v108, v108, v164
	v_mul_f32_e32 v109, v109, v165
	v_mul_f32_e32 v110, v110, v166
	v_mul_f32_e32 v111, v111, v167
	v_cvt_pk_bf16_f32 v168, -v108, -v109
	v_cvt_pk_bf16_f32 v169, -v110, -v111
	ds_write_b64 v115, v[168:169] offset:23872
	ds_read_b128 v[120:123], v116 offset:17408
	ds_read_b128 v[142:145], v116 offset:0
	ds_read_b128 v[124:127], v116 offset:17472
	ds_read_b128 v[146:149], v116 offset:64
	ds_read_b128 v[128:131], v116 offset:17536
	ds_read_b128 v[150:153], v116 offset:128
	ds_read_b128 v[132:135], v116 offset:17600
	ds_read_b128 v[154:157], v116 offset:192
	ds_read_b32 v112, v117 offset:0
	ds_read_b128 v[160:163], v114 offset:0
	v_cmp_le_i32_e64 s[10:11], 0, v119
	v_cmp_le_i32_e64 s[12:13], 1, v119
	v_cmp_le_i32_e64 s[48:49], 2, v119
	v_cmp_le_i32_e64 s[50:51], 3, v119
	s_waitcnt lgkmcnt(8)
	v_mfma_f32_16x16x32_bf16 v[108:111], v[120:123], v[142:145], 0
	s_waitcnt lgkmcnt(6)
	v_mfma_f32_16x16x32_bf16 v[108:111], v[124:127], v[146:149], v[108:111]
	s_waitcnt lgkmcnt(4)
	v_mfma_f32_16x16x32_bf16 v[108:111], v[128:131], v[150:153], v[108:111]
	s_waitcnt lgkmcnt(2)
	v_mfma_f32_16x16x32_bf16 v[108:111], v[132:135], v[154:157], v[108:111]
	s_waitcnt lgkmcnt(0)
	v_sub_f32_e32 v164, v112, v160
	v_sub_f32_e32 v165, v112, v161
	v_sub_f32_e32 v166, v112, v162
	v_sub_f32_e32 v167, v112, v163
	v_mul_f32_e32 v164, 0x3fb8aa3b, v164
	v_mul_f32_e32 v165, 0x3fb8aa3b, v165
	v_mul_f32_e32 v166, 0x3fb8aa3b, v166
	v_mul_f32_e32 v167, 0x3fb8aa3b, v167
	v_exp_f32_e32 v164, v164
	v_exp_f32_e32 v165, v165
	v_exp_f32_e32 v166, v166
	v_exp_f32_e32 v167, v167
	v_mul_f32_e32 v108, v108, v164
	v_mul_f32_e32 v109, v109, v165
	v_mul_f32_e32 v110, v110, v166
	v_mul_f32_e32 v111, v111, v167
	v_cndmask_b32_e64 v108, 0, v108, s[10:11]
	v_cndmask_b32_e64 v109, 0, v109, s[12:13]
	v_cndmask_b32_e64 v110, 0, v110, s[48:49]
	v_cndmask_b32_e64 v111, 0, v111, s[50:51]
	v_cvt_pk_bf16_f32 v168, v108, v109
	v_cvt_pk_bf16_f32 v169, v110, v111
	ds_write_b64 v115, v[168:169] offset:0
	s_branch .Lgt_end
.Lgt_lo:
	s_cmp_lt_u32 s79, 2
	s_cbranch_scc1 .Lgt_01
	s_cmp_eq_u32 s79, 2
	s_cbranch_scc1 .Lgt_w2
	ds_read_b128 v[120:123], v116 offset:17408
	ds_read_b128 v[142:145], v116 offset:30464
	ds_read_b128 v[124:127], v116 offset:17472
	ds_read_b128 v[146:149], v116 offset:30528
	ds_read_b128 v[128:131], v116 offset:17536
	ds_read_b128 v[150:153], v116 offset:30592
	ds_read_b128 v[132:135], v116 offset:17600
	ds_read_b128 v[154:157], v116 offset:30656
	ds_read_b32 v112, v117 offset:192
	ds_read_b32 v113, v117 offset:2240
	ds_read_b128 v[160:163], v114 offset:0
	s_waitcnt lgkmcnt(9)
	v_mfma_f32_16x16x32_bf16 v[108:111], v[120:123], v[142:145], 0
	s_waitcnt lgkmcnt(7)
	v_mfma_f32_16x16x32_bf16 v[108:111], v[124:127], v[146:149], v[108:111]
	s_waitcnt lgkmcnt(5)
	v_mfma_f32_16x16x32_bf16 v[108:111], v[128:131], v[150:153], v[108:111]
	s_waitcnt lgkmcnt(3)
	v_mfma_f32_16x16x32_bf16 v[108:111], v[132:135], v[154:157], v[108:111]
	s_waitcnt lgkmcnt(0)
	v_sub_f32_e32 v164, v112, v160
	v_sub_f32_e32 v165, v112, v161
	v_sub_f32_e32 v166, v112, v162
	v_sub_f32_e32 v167, v112, v163
	v_mul_f32_e32 v164, 0x3fb8aa3b, v164
	v_mul_f32_e32 v165, 0x3fb8aa3b, v165
	v_mul_f32_e32 v166, 0x3fb8aa3b, v166
	v_mul_f32_e32 v167, 0x3fb8aa3b, v167
	v_exp_f32_e32 v164, v164
	v_exp_f32_e32 v165, v165
	v_exp_f32_e32 v166, v166
	v_exp_f32_e32 v167, v167
	v_mul_f32_e32 v108, v108, v113
	v_mul_f32_e32 v109, v109, v113
	v_mul_f32_e32 v110, v110, v113
	v_mul_f32_e32 v111, v111, v113
	v_mul_f32_e32 v108, v108, v164
	v_mul_f32_e32 v109, v109, v165
	v_mul_f32_e32 v110, v110, v166
	v_mul_f32_e32 v111, v111, v167
	v_cvt_pk_bf16_f32 v168, -v108, -v109
	v_cvt_pk_bf16_f32 v169, -v110, -v111
	ds_write_b64 v115, v[168:169] offset:23808
	ds_read_b128 v[120:123], v116 offset:30464
	ds_read_b128 v[142:145], v116 offset:30464
	ds_read_b128 v[124:127], v116 offset:30528
	ds_read_b128 v[146:149], v116 offset:30528
	ds_read_b128 v[128:131], v116 offset:30592
	ds_read_b128 v[150:153], v116 offset:30592
	ds_read_b128 v[132:135], v116 offset:30656
	ds_read_b128 v[154:157], v116 offset:30656
	ds_read_b32 v112, v117 offset:192
	ds_read_b32 v113, v117 offset:2240
	ds_read_b128 v[160:163], v114 offset:192
	v_cmp_lt_i32_e64 s[10:11], 0, v119
	v_cmp_lt_i32_e64 s[12:13], 1, v119
	v_cmp_lt_i32_e64 s[48:49], 2, v119
	v_cmp_lt_i32_e64 s[50:51], 3, v119
	s_waitcnt lgkmcnt(9)
	v_mfma_f32_16x16x32_bf16 v[108:111], v[120:123], v[142:145], 0
	s_waitcnt lgkmcnt(7)
	v_mfma_f32_16x16x32_bf16 v[108:111], v[124:127], v[146:149], v[108:111]
	s_waitcnt lgkmcnt(5)
	v_mfma_f32_16x16x32_bf16 v[108:111], v[128:131], v[150:153], v[108:111]
	s_waitcnt lgkmcnt(3)
	v_mfma_f32_16x16x32_bf16 v[108:111], v[132:135], v[154:157], v[108:111]
	s_waitcnt lgkmcnt(0)
	v_sub_f32_e32 v164, v112, v160
	v_sub_f32_e32 v165, v112, v161
	v_sub_f32_e32 v166, v112, v162
	v_sub_f32_e32 v167, v112, v163
	v_mul_f32_e32 v164, 0x3fb8aa3b, v164
	v_mul_f32_e32 v165, 0x3fb8aa3b, v165
	v_mul_f32_e32 v166, 0x3fb8aa3b, v166
	v_mul_f32_e32 v167, 0x3fb8aa3b, v167
	v_exp_f32_e32 v164, v164
	v_exp_f32_e32 v165, v165
	v_exp_f32_e32 v166, v166
	v_exp_f32_e32 v167, v167
	v_mul_f32_e32 v108, v108, v113
	v_mul_f32_e32 v109, v109, v113
	v_mul_f32_e32 v110, v110, v113
	v_mul_f32_e32 v111, v111, v113
	v_mul_f32_e32 v108, v108, v164
	v_mul_f32_e32 v109, v109, v165
	v_mul_f32_e32 v110, v110, v166
	v_mul_f32_e32 v111, v111, v167
	v_cndmask_b32_e64 v108, 0, v108, s[10:11]
	v_cndmask_b32_e64 v109, 0, v109, s[12:13]
	v_cndmask_b32_e64 v110, 0, v110, s[48:49]
	v_cndmask_b32_e64 v111, 0, v111, s[50:51]
	v_cvt_pk_bf16_f32 v168, -v108, -v109
	v_cvt_pk_bf16_f32 v169, -v110, -v111
	ds_write_b64 v115, v[168:169] offset:23904
	ds_write_b32 v136, v108 offset:0
	ds_write_b32 v136, v109 offset:80
	ds_write_b32 v136, v110 offset:160
	ds_write_b32 v136, v111 offset:240
	s_branch .Lgt_inv
.Lgt_w2:
	ds_read_b128 v[120:123], v116 offset:21760
	ds_read_b128 v[142:145], v116 offset:26112
	ds_read_b128 v[124:127], v116 offset:21824
	ds_read_b128 v[146:149], v116 offset:26176
	ds_read_b128 v[128:131], v116 offset:21888
	ds_read_b128 v[150:153], v116 offset:26240
	ds_read_b128 v[132:135], v116 offset:21952
	ds_read_b128 v[154:157], v116 offset:26304
	ds_read_b32 v112, v117 offset:128
	ds_read_b32 v113, v117 offset:2176
	ds_read_b128 v[160:163], v114 offset:64
	s_waitcnt lgkmcnt(9)
	v_mfma_f32_16x16x32_bf16 v[108:111], v[120:123], v[142:145], 0
	s_waitcnt lgkmcnt(7)
	v_mfma_f32_16x16x32_bf16 v[108:111], v[124:127], v[146:149], v[108:111]
	s_waitcnt lgkmcnt(5)
	v_mfma_f32_16x16x32_bf16 v[108:111], v[128:131], v[150:153], v[108:111]
	s_waitcnt lgkmcnt(3)
	v_mfma_f32_16x16x32_bf16 v[108:111], v[132:135], v[154:157], v[108:111]
	s_waitcnt lgkmcnt(0)
	v_sub_f32_e32 v164, v112, v160
	v_sub_f32_e32 v165, v112, v161
	v_sub_f32_e32 v166, v112, v162
	v_sub_f32_e32 v167, v112, v163
	v_mul_f32_e32 v164, 0x3fb8aa3b, v164
	v_mul_f32_e32 v165, 0x3fb8aa3b, v165
	v_mul_f32_e32 v166, 0x3fb8aa3b, v166
	v_mul_f32_e32 v167, 0x3fb8aa3b, v167
	v_exp_f32_e32 v164, v164
	v_exp_f32_e32 v165, v165
	v_exp_f32_e32 v166, v166
	v_exp_f32_e32 v167, v167
	v_mul_f32_e32 v108, v108, v113
	v_mul_f32_e32 v109, v109, v113
	v_mul_f32_e32 v110, v110, v113
	v_mul_f32_e32 v111, v111, v113
	v_mul_f32_e32 v108, v108, v164
	v_mul_f32_e32 v109, v109, v165
	v_mul_f32_e32 v110, v110, v166
	v_mul_f32_e32 v111, v111, v167
	v_cvt_pk_bf16_f32 v168, -v108, -v109
	v_cvt_pk_bf16_f32 v169, -v110, -v111
	ds_write_b64 v115, v[168:169] offset:21536
	ds_read_b128 v[120:123], v116 offset:26112
	ds_read_b128 v[142:145], v116 offset:26112
	ds_read_b128 v[124:127], v116 offset:26176
	ds_read_b128 v[146:149], v116 offset:26176
	ds_read_b128 v[128:131], v116 offset:26240
	ds_read_b128 v[150:153], v116 offset:26240
	ds_read_b128 v[132:135], v116 offset:26304
	ds_read_b128 v[154:157], v116 offset:26304
	ds_read_b32 v112, v117 offset:128
	ds_read_b32 v113, v117 offset:2176
	ds_read_b128 v[160:163], v114 offset:128
	v_cmp_lt_i32_e64 s[10:11], 0, v119
	v_cmp_lt_i32_e64 s[12:13], 1, v119
	v_cmp_lt_i32_e64 s[48:49], 2, v119
	v_cmp_lt_i32_e64 s[50:51], 3, v119
	s_waitcnt lgkmcnt(9)
	v_mfma_f32_16x16x32_bf16 v[108:111], v[120:123], v[142:145], 0
	s_waitcnt lgkmcnt(7)
	v_mfma_f32_16x16x32_bf16 v[108:111], v[124:127], v[146:149], v[108:111]
	s_waitcnt lgkmcnt(5)
	v_mfma_f32_16x16x32_bf16 v[108:111], v[128:131], v[150:153], v[108:111]
	s_waitcnt lgkmcnt(3)
	v_mfma_f32_16x16x32_bf16 v[108:111], v[132:135], v[154:157], v[108:111]
	s_waitcnt lgkmcnt(0)
	v_sub_f32_e32 v164, v112, v160
	v_sub_f32_e32 v165, v112, v161
	v_sub_f32_e32 v166, v112, v162
	v_sub_f32_e32 v167, v112, v163
	v_mul_f32_e32 v164, 0x3fb8aa3b, v164
	v_mul_f32_e32 v165, 0x3fb8aa3b, v165
	v_mul_f32_e32 v166, 0x3fb8aa3b, v166
	v_mul_f32_e32 v167, 0x3fb8aa3b, v167
	v_exp_f32_e32 v164, v164
	v_exp_f32_e32 v165, v165
	v_exp_f32_e32 v166, v166
	v_exp_f32_e32 v167, v167
	v_mul_f32_e32 v108, v108, v113
	v_mul_f32_e32 v109, v109, v113
	v_mul_f32_e32 v110, v110, v113
	v_mul_f32_e32 v111, v111, v113
	v_mul_f32_e32 v108, v108, v164
	v_mul_f32_e32 v109, v109, v165
	v_mul_f32_e32 v110, v110, v166
	v_mul_f32_e32 v111, v111, v167
	v_cndmask_b32_e64 v108, 0, v108, s[10:11]
	v_cndmask_b32_e64 v109, 0, v109, s[12:13]
	v_cndmask_b32_e64 v110, 0, v110, s[48:49]
	v_cndmask_b32_e64 v111, 0, v111, s[50:51]
	v_cvt_pk_bf16_f32 v168, -v108, -v109
	v_cvt_pk_bf16_f32 v169, -v110, -v111
	ds_write_b64 v115, v[168:169] offset:21568
	ds_write_b32 v136, v108 offset:0
	ds_write_b32 v136, v109 offset:80
	ds_write_b32 v136, v110 offset:160
	ds_write_b32 v136, v111 offset:240
	s_branch .Lgt_inv
.Lgt_01:
	s_cmp_eq_u32 s79, 0
	s_cbranch_scc1 .Lgt_w0
	ds_read_b128 v[120:123], v116 offset:17408
	ds_read_b128 v[142:145], v116 offset:26112
	ds_read_b128 v[124:127], v116 offset:17472
	ds_read_b128 v[146:149], v116 offset:26176
	ds_read_b128 v[128:131], v116 offset:17536
	ds_read_b128 v[150:153], v116 offset:26240
	ds_read_b128 v[132:135], v116 offset:17600
	ds_read_b128 v[154:157], v116 offset:26304
	ds_read_b32 v112, v117 offset:128
	ds_read_b32 v113, v117 offset:2176
	ds_read_b128 v[160:163], v114 offset:0
	s_waitcnt lgkmcnt(9)
	v_mfma_f32_16x16x32_bf16 v[108:111], v[120:123], v[142:145], 0
	s_waitcnt lgkmcnt(7)
	v_mfma_f32_16x16x32_bf16 v[108:111], v[124:127], v[146:149], v[108:111]
	s_waitcnt lgkmcnt(5)
	v_mfma_f32_16x16x32_bf16 v[108:111], v[128:131], v[150:153], v[108:111]
	s_waitcnt lgkmcnt(3)
	v_mfma_f32_16x16x32_bf16 v[108:111], v[132:135], v[154:157], v[108:111]
	s_waitcnt lgkmcnt(0)
	v_sub_f32_e32 v164, v112, v160
	v_sub_f32_e32 v165, v112, v161
	v_sub_f32_e32 v166, v112, v162
	v_sub_f32_e32 v167, v112, v163
	v_mul_f32_e32 v164, 0x3fb8aa3b, v164
	v_mul_f32_e32 v165, 0x3fb8aa3b, v165
	v_mul_f32_e32 v166, 0x3fb8aa3b, v166
	v_mul_f32_e32 v167, 0x3fb8aa3b, v167
	v_exp_f32_e32 v164, v164
	v_exp_f32_e32 v165, v165
	v_exp_f32_e32 v166, v166
	v_exp_f32_e32 v167, v167
	v_mul_f32_e32 v108, v108, v113
	v_mul_f32_e32 v109, v109, v113
	v_mul_f32_e32 v110, v110, v113
	v_mul_f32_e32 v111, v111, v113
	v_mul_f32_e32 v108, v108, v164
	v_mul_f32_e32 v109, v109, v165
	v_mul_f32_e32 v110, v110, v166
	v_mul_f32_e32 v111, v111, v167
	v_cvt_pk_bf16_f32 v168, -v108, -v109
	v_cvt_pk_bf16_f32 v169, -v110, -v111
	ds_write_b64 v115, v[168:169] offset:21504
	ds_read_b128 v[120:123], v116 offset:21760
	ds_read_b128 v[142:145], v116 offset:21760
	ds_read_b128 v[124:127], v116 offset:21824
	ds_read_b128 v[146:149], v116 offset:21824
	ds_read_b128 v[128:131], v116 offset:21888
	ds_read_b128 v[150:153], v116 offset:21888
	ds_read_b128 v[132:135], v116 offset:21952
	ds_read_b128 v[154:157], v116 offset:21952
	ds_read_b32 v112, v117 offset:64
	ds_read_b32 v113, v117 offset:2112
	ds_read_b128 v[160:163], v114 offset:64
	v_cmp_lt_i32_e64 s[10:11], 0, v119
	v_cmp_lt_i32_e64 s[12:13], 1, v119
	v_cmp_lt_i32_e64 s[48:49], 2, v119
	v_cmp_lt_i32_e64 s[50:51], 3, v119
	s_waitcnt lgkmcnt(9)
	v_mfma_f32_16x16x32_bf16 v[108:111], v[120:123], v[142:145], 0
	s_waitcnt lgkmcnt(7)
	v_mfma_f32_16x16x32_bf16 v[108:111], v[124:127], v[146:149], v[108:111]
	s_waitcnt lgkmcnt(5)
	v_mfma_f32_16x16x32_bf16 v[108:111], v[128:131], v[150:153], v[108:111]
	s_waitcnt lgkmcnt(3)
	v_mfma_f32_16x16x32_bf16 v[108:111], v[132:135], v[154:157], v[108:111]
	s_waitcnt lgkmcnt(0)
	v_sub_f32_e32 v164, v112, v160
	v_sub_f32_e32 v165, v112, v161
	v_sub_f32_e32 v166, v112, v162
	v_sub_f32_e32 v167, v112, v163
	v_mul_f32_e32 v164, 0x3fb8aa3b, v164
	v_mul_f32_e32 v165, 0x3fb8aa3b, v165
	v_mul_f32_e32 v166, 0x3fb8aa3b, v166
	v_mul_f32_e32 v167, 0x3fb8aa3b, v167
	v_exp_f32_e32 v164, v164
	v_exp_f32_e32 v165, v165
	v_exp_f32_e32 v166, v166
	v_exp_f32_e32 v167, v167
	v_mul_f32_e32 v108, v108, v113
	v_mul_f32_e32 v109, v109, v113
	v_mul_f32_e32 v110, v110, v113
	v_mul_f32_e32 v111, v111, v113
	v_mul_f32_e32 v108, v108, v164
	v_mul_f32_e32 v109, v109, v165
	v_mul_f32_e32 v110, v110, v166
	v_mul_f32_e32 v111, v111, v167
	v_cndmask_b32_e64 v108, 0, v108, s[10:11]
	v_cndmask_b32_e64 v109, 0, v109, s[12:13]
	v_cndmask_b32_e64 v110, 0, v110, s[48:49]
	v_cndmask_b32_e64 v111, 0, v111, s[50:51]
	v_cvt_pk_bf16_f32 v168, -v108, -v109
	v_cvt_pk_bf16_f32 v169, -v110, -v111
	ds_write_b64 v115, v[168:169] offset:19232
	ds_write_b32 v136, v108 offset:0
	ds_write_b32 v136, v109 offset:80
	ds_write_b32 v136, v110 offset:160
	ds_write_b32 v136, v111 offset:240
	s_branch .Lgt_inv
.Lgt_w0:
	ds_read_b128 v[120:123], v116 offset:17408
	ds_read_b128 v[142:145], v116 offset:21760
	ds_read_b128 v[124:127], v116 offset:17472
	ds_read_b128 v[146:149], v116 offset:21824
	ds_read_b128 v[128:131], v116 offset:17536
	ds_read_b128 v[150:153], v116 offset:21888
	ds_read_b128 v[132:135], v116 offset:17600
	ds_read_b128 v[154:157], v116 offset:21952
	ds_read_b32 v112, v117 offset:64
	ds_read_b32 v113, v117 offset:2112
	ds_read_b128 v[160:163], v114 offset:0
	s_waitcnt lgkmcnt(9)
	v_mfma_f32_16x16x32_bf16 v[108:111], v[120:123], v[142:145], 0
	s_waitcnt lgkmcnt(7)
	v_mfma_f32_16x16x32_bf16 v[108:111], v[124:127], v[146:149], v[108:111]
	s_waitcnt lgkmcnt(5)
	v_mfma_f32_16x16x32_bf16 v[108:111], v[128:131], v[150:153], v[108:111]
	s_waitcnt lgkmcnt(3)
	v_mfma_f32_16x16x32_bf16 v[108:111], v[132:135], v[154:157], v[108:111]
	s_waitcnt lgkmcnt(0)
	v_sub_f32_e32 v164, v112, v160
	v_sub_f32_e32 v165, v112, v161
	v_sub_f32_e32 v166, v112, v162
	v_sub_f32_e32 v167, v112, v163
	v_mul_f32_e32 v164, 0x3fb8aa3b, v164
	v_mul_f32_e32 v165, 0x3fb8aa3b, v165
	v_mul_f32_e32 v166, 0x3fb8aa3b, v166
	v_mul_f32_e32 v167, 0x3fb8aa3b, v167
	v_exp_f32_e32 v164, v164
	v_exp_f32_e32 v165, v165
	v_exp_f32_e32 v166, v166
	v_exp_f32_e32 v167, v167
	v_mul_f32_e32 v108, v108, v113
	v_mul_f32_e32 v109, v109, v113
	v_mul_f32_e32 v110, v110, v113
	v_mul_f32_e32 v111, v111, v113
	v_mul_f32_e32 v108, v108, v164
	v_mul_f32_e32 v109, v109, v165
	v_mul_f32_e32 v110, v110, v166
	v_mul_f32_e32 v111, v111, v167
	v_cvt_pk_bf16_f32 v168, -v108, -v109
	v_cvt_pk_bf16_f32 v169, -v110, -v111
	ds_write_b64 v115, v[168:169] offset:19200
	ds_read_b128 v[120:123], v116 offset:17408
	ds_read_b128 v[142:145], v116 offset:17408
	ds_read_b128 v[124:127], v116 offset:17472
	ds_read_b128 v[146:149], v116 offset:17472
	ds_read_b128 v[128:131], v116 offset:17536
	ds_read_b128 v[150:153], v116 offset:17536
	ds_read_b128 v[132:135], v116 offset:17600
	ds_read_b128 v[154:157], v116 offset:17600
	ds_read_b32 v112, v117 offset:0
	ds_read_b32 v113, v117 offset:2048
	ds_read_b128 v[160:163], v114 offset:0
	v_cmp_lt_i32_e64 s[10:11], 0, v119
	v_cmp_lt_i32_e64 s[12:13], 1, v119
	v_cmp_lt_i32_e64 s[48:49], 2, v119
	v_cmp_lt_i32_e64 s[50:51], 3, v119
	s_waitcnt lgkmcnt(9)
	v_mfma_f32_16x16x32_bf16 v[108:111], v[120:123], v[142:145], 0
	s_waitcnt lgkmcnt(7)
	v_mfma_f32_16x16x32_bf16 v[108:111], v[124:127], v[146:149], v[108:111]
	s_waitcnt lgkmcnt(5)
	v_mfma_f32_16x16x32_bf16 v[108:111], v[128:131], v[150:153], v[108:111]
	s_waitcnt lgkmcnt(3)
	v_mfma_f32_16x16x32_bf16 v[108:111], v[132:135], v[154:157], v[108:111]
	s_waitcnt lgkmcnt(0)
	v_sub_f32_e32 v164, v112, v160
	v_sub_f32_e32 v165, v112, v161
	v_sub_f32_e32 v166, v112, v162
	v_sub_f32_e32 v167, v112, v163
	v_mul_f32_e32 v164, 0x3fb8aa3b, v164
	v_mul_f32_e32 v165, 0x3fb8aa3b, v165
	v_mul_f32_e32 v166, 0x3fb8aa3b, v166
	v_mul_f32_e32 v167, 0x3fb8aa3b, v167
	v_exp_f32_e32 v164, v164
	v_exp_f32_e32 v165, v165
	v_exp_f32_e32 v166, v166
	v_exp_f32_e32 v167, v167
	v_mul_f32_e32 v108, v108, v113
	v_mul_f32_e32 v109, v109, v113
	v_mul_f32_e32 v110, v110, v113
	v_mul_f32_e32 v111, v111, v113
	v_mul_f32_e32 v108, v108, v164
	v_mul_f32_e32 v109, v109, v165
	v_mul_f32_e32 v110, v110, v166
	v_mul_f32_e32 v111, v111, v167
	v_cndmask_b32_e64 v108, 0, v108, s[10:11]
	v_cndmask_b32_e64 v109, 0, v109, s[12:13]
	v_cndmask_b32_e64 v110, 0, v110, s[48:49]
	v_cndmask_b32_e64 v111, 0, v111, s[50:51]
	v_cvt_pk_bf16_f32 v168, -v108, -v109
	v_cvt_pk_bf16_f32 v169, -v110, -v111
	ds_write_b64 v115, v[168:169] offset:16896
	ds_write_b32 v136, v108 offset:0
	ds_write_b32 v136, v109 offset:80
	ds_write_b32 v136, v110 offset:160
	ds_write_b32 v136, v111 offset:240
.Lgt_inv:
	v_cmp_gt_u32_e32 vcc, 16, v3
	s_and_saveexec_b64 s[10:11], vcc
	s_cbranch_execz .Lgt_invend
	v_mov_b32_e32 v119, s97
	ds_read_b128 v[120:123], v119 offset:0
	ds_read_b128 v[124:127], v119 offset:16
	ds_read_b128 v[128:131], v119 offset:32
	ds_read_b128 v[132:135], v119 offset:48
	ds_read_b128 v[142:145], v119 offset:80
	ds_read_b128 v[146:149], v119 offset:96
	ds_read_b128 v[150:153], v119 offset:112
	ds_read_b128 v[154:157], v119 offset:128
	ds_read_b128 v[158:161], v119 offset:160
	ds_read_b128 v[236:239], v119 offset:176
	ds_read_b128 v[240:243], v119 offset:192
	ds_read_b128 v[244:247], v119 offset:208
	ds_read_b128 v[248:251], v119 offset:256
	ds_read_b128 v[252:255], v119 offset:272
	ds_read_b128 v[108:111], v119 offset:288
	ds_read_b128 v[112:115], v119 offset:336
	v_cmp_eq_u32_e64 s[12:13], 0, v3
	v_cmp_eq_u32_e64 s[48:49], 1, v3
	v_cmp_eq_u32_e64 s[50:51], 2, v3
	v_cndmask_b32_e64 v210, 0, 1.0, s[12:13]
	v_cmp_eq_u32_e64 s[12:13], 3, v3
	v_cndmask_b32_e64 v211, 0, 1.0, s[48:49]
	v_cmp_eq_u32_e64 s[48:49], 4, v3
	v_cndmask_b32_e64 v212, 0, 1.0, s[50:51]
	v_cmp_eq_u32_e64 s[50:51], 5, v3
	v_cndmask_b32_e64 v213, 0, 1.0, s[12:13]
	v_cmp_eq_u32_e64 s[12:13], 6, v3
	v_cndmask_b32_e64 v214, 0, 1.0, s[48:49]
	v_cmp_eq_u32_e64 s[48:49], 7, v3
	v_cndmask_b32_e64 v215, 0, 1.0, s[50:51]
	v_cmp_eq_u32_e64 s[50:51], 8, v3
	v_cndmask_b32_e64 v216, 0, 1.0, s[12:13]
	v_cmp_eq_u32_e64 s[12:13], 9, v3
	v_cndmask_b32_e64 v217, 0, 1.0, s[48:49]
	v_cmp_eq_u32_e64 s[48:49], 10, v3
	v_cndmask_b32_e64 v218, 0, 1.0, s[50:51]
	v_cmp_eq_u32_e64 s[50:51], 11, v3
	v_cndmask_b32_e64 v219, 0, 1.0, s[12:13]
	v_cmp_eq_u32_e64 s[12:13], 12, v3
	v_cndmask_b32_e64 v187, 0, 1.0, s[48:49]
	v_cmp_eq_u32_e64 s[48:49], 13, v3
	v_cndmask_b32_e64 v164, 0, 1.0, s[50:51]
	v_cmp_eq_u32_e64 s[50:51], 14, v3
	v_cndmask_b32_e64 v165, 0, 1.0, s[12:13]
	v_cmp_eq_u32_e64 s[12:13], 15, v3
	v_cndmask_b32_e64 v166, 0, 1.0, s[48:49]
	s_nop 0
	v_cndmask_b32_e64 v167, 0, 1.0, s[50:51]
	v_cndmask_b32_e64 v168, 0, 1.0, s[12:13]
	s_waitcnt lgkmcnt(15)
	v_fma_f32 v211, -v121, v210, v211
	v_fma_f32 v212, -v122, v210, v212
	v_fma_f32 v213, -v123, v210, v213
	ds_read_b128 v[120:123], v119 offset:352
	s_waitcnt lgkmcnt(15)
	v_fma_f32 v214, -v124, v210, v214
	v_fma_f32 v215, -v125, v210, v215
	v_fma_f32 v216, -v126, v210, v216
	v_fma_f32 v217, -v127, v210, v217
	ds_read_b128 v[124:127], v119 offset:368
	s_waitcnt lgkmcnt(15)
	v_fma_f32 v218, -v128, v210, v218
	v_fma_f32 v219, -v129, v210, v219
	v_fma_f32 v187, -v130, v210, v187
	v_fma_f32 v164, -v131, v210, v164
	ds_read_b128 v[128:131], v119 offset:416
	s_waitcnt lgkmcnt(15)
	v_fma_f32 v165, -v132, v210, v165
	v_fma_f32 v166, -v133, v210, v166
	v_fma_f32 v167, -v134, v210, v167
	v_fma_f32 v168, -v135, v210, v168
	ds_read_b128 v[132:135], v119 offset:432
	s_waitcnt lgkmcnt(15)
	v_fma_f32 v212, -v144, v211, v212
	v_fma_f32 v213, -v145, v211, v213
	ds_read_b128 v[142:145], v119 offset:448
	s_waitcnt lgkmcnt(15)
	v_fma_f32 v214, -v146, v211, v214
	v_fma_f32 v215, -v147, v211, v215
	v_fma_f32 v216, -v148, v211, v216
	v_fma_f32 v217, -v149, v211, v217
	ds_read_b128 v[146:149], v119 offset:496
	s_waitcnt lgkmcnt(15)
	v_fma_f32 v218, -v150, v211, v218
	v_fma_f32 v219, -v151, v211, v219
	v_fma_f32 v187, -v152, v211, v187
	v_fma_f32 v164, -v153, v211, v164
	ds_read_b128 v[150:153], v119 offset:512
	s_waitcnt lgkmcnt(15)
	v_fma_f32 v165, -v154, v211, v165
	v_fma_f32 v166, -v155, v211, v166
	v_fma_f32 v167, -v156, v211, v167
	v_fma_f32 v168, -v157, v211, v168
	ds_read_b128 v[154:157], v119 offset:528
	s_waitcnt lgkmcnt(15)
	v_fma_f32 v213, -v161, v212, v213
	ds_read_b128 v[158:161], v119 offset:592
	s_waitcnt lgkmcnt(15)
	v_fma_f32 v214, -v236, v212, v214
	v_fma_f32 v215, -v237, v212, v215
	v_fma_f32 v216, -v238, v212, v216
	v_fma_f32 v217, -v239, v212, v217
	ds_read_b128 v[236:239], v119 offset:608
	s_waitcnt lgkmcnt(15)
	v_fma_f32 v218, -v240, v212, v218
	v_fma_f32 v219, -v241, v212, v219
	v_fma_f32 v187, -v242, v212, v187
	v_fma_f32 v164, -v243, v212, v164
	ds_read_b128 v[240:243], v119 offset:672
	s_waitcnt lgkmcnt(15)
	v_fma_f32 v165, -v244, v212, v165
	v_fma_f32 v166, -v245, v212, v166
	v_fma_f32 v167, -v246, v212, v167
	v_fma_f32 v168, -v247, v212, v168
	ds_read_b128 v[244:247], v119 offset:688
	s_waitcnt lgkmcnt(15)
	v_fma_f32 v214, -v248, v213, v214
	v_fma_f32 v215, -v249, v213, v215
	v_fma_f32 v216, -v250, v213, v216
	v_fma_f32 v217, -v251, v213, v217
	ds_read_b128 v[248:251], v119 offset:752
	s_waitcnt lgkmcnt(15)
	v_fma_f32 v218, -v252, v213, v218
	v_fma_f32 v219, -v253, v213, v219
	v_fma_f32 v187, -v254, v213, v187
	v_fma_f32 v164, -v255, v213, v164
	ds_read_b128 v[252:255], v119 offset:768
	s_waitcnt lgkmcnt(15)
	v_fma_f32 v165, -v108, v213, v165
	v_fma_f32 v166, -v109, v213, v166
	v_fma_f32 v167, -v110, v213, v167
	v_fma_f32 v168, -v111, v213, v168
	ds_read_b128 v[108:111], v119 offset:832
	s_waitcnt lgkmcnt(15)
	v_fma_f32 v215, -v113, v214, v215
	v_fma_f32 v216, -v114, v214, v216
	v_fma_f32 v217, -v115, v214, v217
	ds_read_b128 v[112:115], v119 offset:848
	s_waitcnt lgkmcnt(15)
	v_fma_f32 v218, -v120, v214, v218
	v_fma_f32 v219, -v121, v214, v219
	v_fma_f32 v187, -v122, v214, v187
	v_fma_f32 v164, -v123, v214, v164
	ds_read_b128 v[120:123], v119 offset:928
	s_waitcnt lgkmcnt(15)
	v_fma_f32 v165, -v124, v214, v165
	v_fma_f32 v166, -v125, v214, v166
	v_fma_f32 v167, -v126, v214, v167
	v_fma_f32 v168, -v127, v214, v168
	ds_read_b128 v[124:127], v119 offset:1008
	s_waitcnt lgkmcnt(15)
	v_fma_f32 v216, -v130, v215, v216
	v_fma_f32 v217, -v131, v215, v217
	ds_read_b128 v[128:131], v119 offset:1088
	s_waitcnt lgkmcnt(15)
	v_fma_f32 v218, -v132, v215, v218
	v_fma_f32 v219, -v133, v215, v219
	v_fma_f32 v187, -v134, v215, v187
	v_fma_f32 v164, -v135, v215, v164
	ds_read_b128 v[132:135], v119 offset:1168
	s_waitcnt lgkmcnt(15)
	v_fma_f32 v165, -v142, v215, v165
	v_fma_f32 v166, -v143, v215, v166
	v_fma_f32 v167, -v144, v215, v167
	v_fma_f32 v168, -v145, v215, v168
	s_waitcnt lgkmcnt(14)
	v_fma_f32 v217, -v149, v216, v217
	s_waitcnt lgkmcnt(13)
	v_fma_f32 v218, -v150, v216, v218
	v_fma_f32 v219, -v151, v216, v219
	v_fma_f32 v187, -v152, v216, v187
	v_fma_f32 v164, -v153, v216, v164
	s_waitcnt lgkmcnt(12)
	v_fma_f32 v165, -v154, v216, v165
	v_fma_f32 v166, -v155, v216, v166
	v_fma_f32 v167, -v156, v216, v167
	v_fma_f32 v168, -v157, v216, v168
	s_waitcnt lgkmcnt(11)
	v_fma_f32 v218, -v158, v217, v218
	v_fma_f32 v219, -v159, v217, v219
	v_fma_f32 v187, -v160, v217, v187
	v_fma_f32 v164, -v161, v217, v164
	s_waitcnt lgkmcnt(10)
	v_fma_f32 v165, -v236, v217, v165
	v_fma_f32 v166, -v237, v217, v166
	v_fma_f32 v167, -v238, v217, v167
	v_fma_f32 v168, -v239, v217, v168
	s_waitcnt lgkmcnt(9)
	v_fma_f32 v219, -v241, v218, v219
	v_fma_f32 v187, -v242, v218, v187
	v_fma_f32 v164, -v243, v218, v164
	s_waitcnt lgkmcnt(8)
	v_fma_f32 v165, -v244, v218, v165
	v_fma_f32 v166, -v245, v218, v166
	v_fma_f32 v167, -v246, v218, v167
	v_fma_f32 v168, -v247, v218, v168
	s_waitcnt lgkmcnt(7)
	v_fma_f32 v187, -v250, v219, v187
	v_fma_f32 v164, -v251, v219, v164
	s_waitcnt lgkmcnt(6)
	v_fma_f32 v165, -v252, v219, v165
	v_fma_f32 v166, -v253, v219, v166
	v_fma_f32 v167, -v254, v219, v167
	v_fma_f32 v168, -v255, v219, v168
	s_waitcnt lgkmcnt(5)
	v_fma_f32 v164, -v111, v187, v164
	s_waitcnt lgkmcnt(4)
	v_fma_f32 v165, -v112, v187, v165
	v_fma_f32 v166, -v113, v187, v166
	v_fma_f32 v167, -v114, v187, v167
	v_fma_f32 v168, -v115, v187, v168
	s_waitcnt lgkmcnt(3)
	v_fma_f32 v165, -v120, v164, v165
	v_fma_f32 v166, -v121, v164, v166
	v_fma_f32 v167, -v122, v164, v167
	v_fma_f32 v168, -v123, v164, v168
	s_waitcnt lgkmcnt(2)
	v_fma_f32 v166, -v125, v165, v166
	v_fma_f32 v167, -v126, v165, v167
	v_fma_f32 v168, -v127, v165, v168
	s_waitcnt lgkmcnt(1)
	v_fma_f32 v167, -v130, v166, v167
	v_fma_f32 v168, -v131, v166, v168
	s_waitcnt lgkmcnt(0)
	v_fma_f32 v168, -v135, v167, v168
	v_lshl_add_u32 v169, v3, 1, s88
	v_cvt_pk_bf16_f32 v170, v210, s0
	ds_write_b16 v169, v170 offset:0
	v_cvt_pk_bf16_f32 v171, v211, s0
	ds_write_b16 v169, v171 offset:40
	v_cvt_pk_bf16_f32 v170, v212, s0
	ds_write_b16 v169, v170 offset:80
	v_cvt_pk_bf16_f32 v171, v213, s0
	ds_write_b16 v169, v171 offset:120
	v_cvt_pk_bf16_f32 v170, v214, s0
	ds_write_b16 v169, v170 offset:160
	v_cvt_pk_bf16_f32 v171, v215, s0
	ds_write_b16 v169, v171 offset:200
	v_cvt_pk_bf16_f32 v170, v216, s0
	ds_write_b16 v169, v170 offset:240
	v_cvt_pk_bf16_f32 v171, v217, s0
	ds_write_b16 v169, v171 offset:280
	v_cvt_pk_bf16_f32 v170, v218, s0
	ds_write_b16 v169, v170 offset:320
	v_cvt_pk_bf16_f32 v171, v219, s0
	ds_write_b16 v169, v171 offset:360
	v_cvt_pk_bf16_f32 v170, v187, s0
	ds_write_b16 v169, v170 offset:400
	v_cvt_pk_bf16_f32 v171, v164, s0
	ds_write_b16 v169, v171 offset:440
	v_cvt_pk_bf16_f32 v170, v165, s0
	ds_write_b16 v169, v170 offset:480
	v_cvt_pk_bf16_f32 v171, v166, s0
	ds_write_b16 v169, v171 offset:520
	v_cvt_pk_bf16_f32 v170, v167, s0
	ds_write_b16 v169, v170 offset:560
	v_cvt_pk_bf16_f32 v171, v168, s0
	ds_write_b16 v169, v171 offset:600

.Lgt_end:
.LBB0_403:
	v_lshrrev_b32_e32 v210, 3, v206
	v_bitop3_b32 v108, v210, v207, s86 bitop3:0x36
	v_mul_u32_u24_e32 v213, 0x90, v206
	s_add_i32 s12, 0, 0x1e600
	v_or_b32_e32 v0, s86, v210
	s_add_i32 s10, 0, 0x21e00
	v_lshlrev_b32_e32 v141, 3, v108
	v_mul_u32_u24_e32 v108, 40, v206
	v_bitop3_b32 v109, v207, v0, 4 bitop3:0x36
	v_add3_u32 v120, s12, v213, v209
	s_waitcnt lgkmcnt(0)
	s_barrier
	v_add3_u32 v108, s10, v208, v108
	v_mul_lo_u32 v113, v118, s76
	v_bitop3_b32 v110, v207, v0, 8 bitop3:0x36
	ds_read2_b64 v[124:127], v108 offset1:80
	ds_read2_b64 v[128:131], v108 offset0:160 offset1:240
	v_lshlrev_b32_e32 v148, 3, v109
	v_add_u32_e32 v108, 0x1000, v120
	v_add_u32_e32 v121, s65, v113
	v_lshlrev_b32_e32 v112, 3, v110
	ds_read2_b64 v[132:135], v108 offset0:64 offset1:68
	v_add_u32_e32 v108, v121, v141
	v_add_u32_e32 v110, v121, v148
	ds_read_b64 v[150:151], v120 offset:2304
	ds_read_b64 v[108:109], v108
	ds_read_b64 v[110:111], v110
	ds_read_b64 v[152:153], v120 offset:6976
	s_waitcnt lgkmcnt(2)
	v_mfma_f32_16x16x16_bf16 v[116:119], v[124:125], v[108:109], 0
	v_add_u32_e32 v114, v121, v112
	s_waitcnt lgkmcnt(1)
	v_lshlrev_b32_e32 v108, 16, v110
	v_and_b32_e32 v109, 0xffff0000, v110
	s_nop 3
	v_cvt_pk_bf16_f32 v142, v116, v117
	v_cvt_pk_bf16_f32 v143, v118, v119
	v_lshlrev_b32_e32 v110, 16, v111
	v_and_b32_e32 v111, 0xffff0000, v111
	ds_read_b64 v[114:115], v114
	v_bitop3_b32 v0, v207, v0, 12 bitop3:0x36
	v_mfma_f32_16x16x16_bf16 v[108:111], v[150:151], v[142:143], v[108:111]
	v_lshlrev_b32_e32 v0, 3, v0
	v_add_u32_e32 v149, 0, v113
	v_add_u32_e32 v121, v121, v0
	v_add_u32_e32 v112, v149, v112
	v_add_u32_e32 v0, v149, v0
	s_nop 2
	v_cvt_pk_bf16_f32 v108, v108, v109
	v_cvt_pk_bf16_f32 v109, v110, v111
	ds_read_b64 v[144:145], v121
	ds_read_b64 v[154:155], v0 offset:34816
	ds_read_b64 v[156:157], v112 offset:34816
	v_mfma_f32_16x16x16_bf16 v[108:111], v[126:127], v[108:109], 0
	s_waitcnt lgkmcnt(3)
	v_lshlrev_b32_e32 v112, 16, v114
	v_and_b32_e32 v113, 0xffff0000, v114
	v_lshlrev_b32_e32 v114, 16, v115
	v_and_b32_e32 v115, 0xffff0000, v115
	v_add_u32_e32 v0, 0x1800, v120
	ds_read2_b64 v[136:139], v0 offset0:96 offset1:100
	v_mfma_f32_16x16x16_bf16 v[112:115], v[132:133], v[142:143], v[112:115]
	v_cvt_pk_bf16_f32 v146, v108, v109
	v_cvt_pk_bf16_f32 v147, v110, v111
	v_add_u32_e32 v0, v149, v141
	v_mul_u32_u24_e32 v211, 0x440, v207
	v_mfma_f32_16x16x16_bf16 v[112:115], v[134:135], v[146:147], v[112:115]
	v_lshlrev_b32_e32 v212, 1, v206
	s_add_i32 s13, s94, 1
	s_cmp_lt_u32 s13, s85
	s_nop 4
	v_cvt_pk_bf16_f32 v112, v112, v113
	v_cvt_pk_bf16_f32 v113, v114, v115
	s_waitcnt lgkmcnt(3)
	v_lshlrev_b32_e32 v114, 16, v145
	v_and_b32_e32 v115, 0xffff0000, v145
	v_mfma_f32_16x16x16_bf16 v[120:123], v[128:129], v[112:113], 0
	v_lshlrev_b32_e32 v112, 16, v144
	v_and_b32_e32 v113, 0xffff0000, v144
	s_waitcnt lgkmcnt(0)
	s_nop 0
	v_mfma_f32_16x16x16_bf16 v[112:115], v[136:137], v[142:143], v[112:115]
	s_nop 2
	v_cvt_pk_bf16_f32 v142, v120, v121
	v_cvt_pk_bf16_f32 v143, v122, v123
	v_mfma_f32_16x16x16_bf16 v[112:115], v[138:139], v[146:147], v[112:115]
	s_nop 0
	v_mfma_f32_16x16x16_bf16 v[112:115], v[152:153], v[142:143], v[112:115]
	ds_read_b64 v[142:143], v0 offset:34816
	v_add_u32_e32 v0, v149, v148
	ds_read_b64 v[148:149], v0 offset:34816
	s_waitcnt lgkmcnt(1)
	v_mfma_f32_16x16x16_bf16 v[142:145], v[124:125], v[142:143], 0
	s_waitcnt lgkmcnt(0)
	v_lshlrev_b32_e32 v146, 16, v148
	v_and_b32_e32 v147, 0xffff0000, v148
	s_nop 4
	v_cvt_pk_bf16_f32 v158, v142, v143
	v_cvt_pk_bf16_f32 v159, v144, v145
	v_lshlrev_b32_e32 v148, 16, v149
	v_and_b32_e32 v149, 0xffff0000, v149
	v_cvt_pk_bf16_f32 v112, v112, v113
	v_cvt_pk_bf16_f32 v113, v114, v115
	v_mfma_f32_16x16x16_bf16 v[146:149], v[150:151], v[158:159], v[146:149]
	v_cvt_pk_bf16_f32 v0, -v142, s0
	v_mfma_f32_16x16x16_bf16 v[112:115], v[130:131], v[112:113], 0
	s_nop 5
	v_cvt_pk_bf16_f32 v124, v146, v147
	v_cvt_pk_bf16_f32 v125, v148, v149
	v_lshlrev_b32_e32 v146, 16, v156
	v_and_b32_e32 v147, 0xffff0000, v156
	v_mfma_f32_16x16x16_bf16 v[124:127], v[126:127], v[124:125], 0
	v_lshlrev_b32_e32 v148, 16, v157
	v_and_b32_e32 v149, 0xffff0000, v157
	s_nop 1
	v_mfma_f32_16x16x16_bf16 v[146:149], v[132:133], v[158:159], v[146:149]
	s_nop 2
	v_cvt_pk_bf16_f32 v150, v124, v125
	v_cvt_pk_bf16_f32 v151, v126, v127
	s_nop 1
	v_mfma_f32_16x16x16_bf16 v[132:135], v[134:135], v[150:151], v[146:149]
	s_nop 2
	v_lshlrev_b32_e32 v146, 16, v154
	v_and_b32_e32 v147, 0xffff0000, v154
	v_lshlrev_b32_e32 v148, 16, v155
	v_and_b32_e32 v149, 0xffff0000, v155
	s_nop 0
	v_cvt_pk_bf16_f32 v132, v132, v133
	v_cvt_pk_bf16_f32 v133, v134, v135
	v_mfma_f32_16x16x16_bf16 v[146:149], v[136:137], v[158:159], v[146:149]
	s_nop 0
	v_mfma_f32_16x16x16_bf16 v[132:135], v[128:129], v[132:133], 0
	v_mfma_f32_16x16x16_bf16 v[136:139], v[138:139], v[150:151], v[146:149]
	s_nop 6
	v_cvt_pk_bf16_f32 v128, v132, v133
	v_cvt_pk_bf16_f32 v129, v134, v135
	s_nop 1
	v_mfma_f32_16x16x16_bf16 v[136:139], v[152:153], v[128:129], v[136:139]
	s_nop 7
	v_cvt_pk_bf16_f32 v128, v136, v137
	v_cvt_pk_bf16_f32 v129, v138, v139
	v_add3_u32 v136, s95, v211, v212
	ds_write_b16 v136, v0
	v_mfma_f32_16x16x16_bf16 v[128:131], v[130:131], v[128:129], 0
	v_cvt_pk_bf16_f32 v0, -v124, s0
	ds_write_b16 v136, v0 offset:4352
	v_cvt_pk_bf16_f32 v0, -v132, s0
	ds_write_b16 v136, v0 offset:8704
	s_nop 3
	v_cvt_pk_bf16_f32 v0, -v128, s0
	ds_write_b16 v136, v0 offset:13056
	v_cvt_pk_bf16_f32 v0, -v143, s0
	ds_write_b16 v136, v0 offset:272
	v_cvt_pk_bf16_f32 v0, -v125, s0
	ds_write_b16 v136, v0 offset:4624
	v_cvt_pk_bf16_f32 v0, -v133, s0
	ds_write_b16 v136, v0 offset:8976
	v_cvt_pk_bf16_f32 v0, -v129, s0
	ds_write_b16 v136, v0 offset:13328
	v_cvt_pk_bf16_f32 v0, -v144, s0
	ds_write_b16 v136, v0 offset:544
	v_cvt_pk_bf16_f32 v0, -v126, s0
	ds_write_b16 v136, v0 offset:4896
	v_cvt_pk_bf16_f32 v0, -v134, s0
	ds_write_b16 v136, v0 offset:9248
	v_cvt_pk_bf16_f32 v0, -v130, s0
	ds_write_b16 v136, v0 offset:13600
	v_cvt_pk_bf16_f32 v0, -v145, s0
	ds_write_b16 v136, v0 offset:816
	v_cvt_pk_bf16_f32 v0, -v127, s0
	ds_write_b16 v136, v0 offset:5168
	v_cvt_pk_bf16_f32 v0, -v135, s0
	ds_write_b16 v136, v0 offset:9520
	v_cvt_pk_bf16_f32 v0, -v131, s0
	ds_write_b16 v136, v0 offset:13872
	s_waitcnt lgkmcnt(0)
	s_barrier
	s_cbranch_scc0 .LBB0_409
	s_and_b64 vcc, exec, s[6:7]
	s_cbranch_vccnz .LBB0_409
	s_lshl_b32 s48, s13, 6
	v_add_u32_e32 v0, s48, v140
	v_xad_u32 v84, v0, -1, s80
	v_cndmask_b32_e64 v84, v84, v0, s[4:5]
	v_add_u32_e32 v0, 1, v0
	v_xad_u32 v85, v0, -1, s80
	v_cndmask_b32_e64 v0, v85, v0, s[4:5]
	v_min_i32_e32 v181, v84, v0
	v_add_u32_e32 v0, v181, v177
	v_mad_i64_i32 v[84:85], s[10:11], v0, s60, v[182:183]
	v_lshlrev_b32_e32 v0, 4, v205
	v_and_b32_e32 v0, 0xf0, v0
	v_lshl_add_u64 v[186:187], v[84:85], 0, v[0:1]
	s_and_b64 vcc, exec, s[6:7]
	s_mov_b64 s[10:11], -1
	s_cbranch_vccnz .LBB0_406
	v_add_u32_e32 v0, -2, v181
	v_cmp_gt_u32_e64 s[10:11], s43, v0
	v_add_u32_e32 v0, -1, v181
	s_nop 0
	v_cndmask_b32_e64 v85, 0, -1, s[10:11]
	v_cndmask_b32_e64 v84, 0, v192, s[10:11]
	v_lshl_add_u64 v[92:93], v[186:187], 0, v[84:85]
	global_load_dwordx4 v[84:87], v[92:93], off
	global_load_dwordx4 v[88:91], v[92:93], off offset:2048
	v_add_co_u32_e32 v92, vcc, 0x1000, v92
	s_waitcnt vmcnt(1)
	v_cndmask_b32_e64 v129, 0, v85, s[10:11]
	v_addc_co_u32_e32 v93, vcc, 0, v93, vcc
	global_load_dwordx4 v[92:95], v[92:93], off
	v_cmp_gt_u32_e32 vcc, s43, v0
	v_cndmask_b32_e64 v128, 0, v84, s[10:11]
	v_cndmask_b32_e64 v131, 0, v87, s[10:11]
	v_cndmask_b32_e64 v85, 0, -1, vcc
	v_cndmask_b32_e32 v84, 0, v193, vcc
	v_cndmask_b32_e64 v130, 0, v86, s[10:11]
	s_waitcnt vmcnt(1)
	v_cndmask_b32_e64 v127, 0, v91, s[10:11]
	v_cndmask_b32_e64 v126, 0, v90, s[10:11]
	v_cndmask_b32_e64 v125, 0, v89, s[10:11]
	v_cndmask_b32_e64 v124, 0, v88, s[10:11]
	v_add_u32_e32 v0, 1, v181
	s_waitcnt vmcnt(0)
	v_cndmask_b32_e64 v133, 0, v93, s[10:11]
	v_cndmask_b32_e64 v132, 0, v92, s[10:11]
	v_lshl_add_u64 v[92:93], v[186:187], 0, v[84:85]
	v_cndmask_b32_e64 v135, 0, v95, s[10:11]
	v_cndmask_b32_e64 v134, 0, v94, s[10:11]
	global_load_dwordx4 v[84:87], v[92:93], off
	global_load_dwordx4 v[88:91], v[92:93], off offset:2048
	v_add_co_u32_e64 v92, s[10:11], s59, v92
	s_waitcnt vmcnt(1)
	v_cndmask_b32_e32 v143, 0, v87, vcc
	v_addc_co_u32_e64 v93, s[10:11], 0, v93, s[10:11]
	global_load_dwordx4 v[92:95], v[92:93], off
	v_cndmask_b32_e32 v142, 0, v86, vcc
	v_cndmask_b32_e32 v141, 0, v85, vcc
	v_cndmask_b32_e32 v140, 0, v84, vcc
	s_waitcnt vmcnt(1)
	v_cndmask_b32_e32 v139, 0, v91, vcc
	v_cndmask_b32_e32 v138, 0, v90, vcc
	v_cndmask_b32_e32 v137, 0, v89, vcc
	v_cndmask_b32_e32 v136, 0, v88, vcc
	global_load_dwordx4 v[84:87], v[186:187], off
	global_load_dwordx4 v[88:91], v[186:187], off offset:2048
	s_waitcnt vmcnt(2)
	v_cndmask_b32_e32 v144, 0, v92, vcc
	v_add_co_u32_e64 v92, s[10:11], s59, v186
	v_cndmask_b32_e32 v145, 0, v93, vcc
	s_nop 0
	v_addc_co_u32_e64 v93, s[10:11], 0, v187, s[10:11]
	v_cndmask_b32_e32 v147, 0, v95, vcc
	v_cndmask_b32_e32 v146, 0, v94, vcc
	global_load_dwordx4 v[92:95], v[92:93], off
	v_cmp_gt_u32_e32 vcc, s43, v181
	s_waitcnt vmcnt(2)
	s_nop 0
	v_cndmask_b32_e32 v87, 0, v87, vcc
	v_cndmask_b32_e32 v86, 0, v86, vcc
	v_cndmask_b32_e32 v85, 0, v85, vcc
	v_cndmask_b32_e32 v84, 0, v84, vcc
	s_waitcnt vmcnt(1)
	v_cndmask_b32_e32 v91, 0, v91, vcc
	v_cndmask_b32_e32 v90, 0, v90, vcc
	v_cndmask_b32_e32 v89, 0, v89, vcc
	v_cndmask_b32_e32 v88, 0, v88, vcc
	s_waitcnt vmcnt(0)
	v_cndmask_b32_e32 v95, 0, v95, vcc
	v_cndmask_b32_e32 v94, 0, v94, vcc
	v_cndmask_b32_e32 v93, 0, v93, vcc
	v_cndmask_b32_e32 v92, 0, v92, vcc
	v_cmp_gt_u32_e32 vcc, s43, v0
	s_nop 1
	v_cndmask_b32_e32 v0, 0, v194, vcc
	v_lshl_add_u64 v[104:105], v[186:187], 0, v[0:1]
	global_load_dwordx4 v[96:99], v[104:105], off
	global_load_dwordx4 v[100:103], v[104:105], off offset:2048
	v_add_co_u32_e64 v104, s[10:11], s59, v104
	v_add_u32_e32 v0, 2, v181
	s_nop 0
	v_addc_co_u32_e64 v105, s[10:11], 0, v105, s[10:11]
	global_load_dwordx4 v[104:107], v[104:105], off
	s_waitcnt vmcnt(2)
	v_cndmask_b32_e32 v99, 0, v99, vcc
	v_cndmask_b32_e32 v98, 0, v98, vcc
	v_cndmask_b32_e32 v97, 0, v97, vcc
	v_cndmask_b32_e32 v96, 0, v96, vcc
	s_waitcnt vmcnt(1)
	v_cndmask_b32_e32 v103, 0, v103, vcc
	v_cndmask_b32_e32 v102, 0, v102, vcc
	v_cndmask_b32_e32 v101, 0, v101, vcc
	v_cndmask_b32_e32 v100, 0, v100, vcc
	s_waitcnt vmcnt(0)
	v_cndmask_b32_e32 v107, 0, v107, vcc
	v_cndmask_b32_e32 v106, 0, v106, vcc
	v_cndmask_b32_e32 v105, 0, v105, vcc
	v_cndmask_b32_e32 v104, 0, v104, vcc
	v_cmp_gt_u32_e32 vcc, s43, v0
	s_nop 1
	v_cndmask_b32_e32 v0, 0, v195, vcc
	v_lshl_add_u64 v[156:157], v[186:187], 0, v[0:1]
	global_load_dwordx4 v[148:151], v[156:157], off
	global_load_dwordx4 v[152:155], v[156:157], off offset:2048
	v_add_co_u32_e64 v156, s[10:11], s59, v156
	v_add_u32_e32 v0, 3, v181
	s_nop 0
	v_addc_co_u32_e64 v157, s[10:11], 0, v157, s[10:11]
	global_load_dwordx4 v[160:163], v[156:157], off
	s_waitcnt vmcnt(2)
	v_cndmask_b32_e32 v159, 0, v151, vcc
	v_cndmask_b32_e32 v158, 0, v150, vcc
	v_cndmask_b32_e32 v157, 0, v149, vcc
	v_cndmask_b32_e32 v156, 0, v148, vcc
	s_waitcnt vmcnt(1)
	v_cndmask_b32_e32 v155, 0, v155, vcc
	v_cndmask_b32_e32 v154, 0, v154, vcc
	v_cndmask_b32_e32 v153, 0, v153, vcc
	v_cndmask_b32_e32 v152, 0, v152, vcc
	s_waitcnt vmcnt(0)
	v_cndmask_b32_e32 v151, 0, v163, vcc
	v_cndmask_b32_e32 v150, 0, v162, vcc
	v_cndmask_b32_e32 v149, 0, v161, vcc
	v_cndmask_b32_e32 v148, 0, v160, vcc
	v_cmp_gt_u32_e32 vcc, s43, v0
	s_nop 1
	v_cndmask_b32_e32 v0, 0, v196, vcc
	v_lshl_add_u64 v[160:161], v[186:187], 0, v[0:1]
	global_load_dwordx4 v[168:171], v[160:161], off
	global_load_dwordx4 v[164:167], v[160:161], off offset:2048
	v_add_co_u32_e64 v160, s[10:11], s59, v160
	s_waitcnt vmcnt(1)
	v_cndmask_b32_e32 v171, 0, v171, vcc
	v_addc_co_u32_e64 v161, s[10:11], 0, v161, s[10:11]
	global_load_dwordx4 v[160:163], v[160:161], off
	v_cndmask_b32_e32 v170, 0, v170, vcc
	v_cndmask_b32_e32 v169, 0, v169, vcc
	v_cndmask_b32_e32 v168, 0, v168, vcc
	s_waitcnt vmcnt(1)
	v_cndmask_b32_e32 v167, 0, v167, vcc
	v_cndmask_b32_e32 v166, 0, v166, vcc
	v_cndmask_b32_e32 v165, 0, v165, vcc
	v_cndmask_b32_e32 v164, 0, v164, vcc
	s_mov_b64 s[10:11], 0
	s_waitcnt vmcnt(0)
	v_cndmask_b32_e32 v163, 0, v163, vcc
	v_cndmask_b32_e32 v162, 0, v162, vcc
	v_cndmask_b32_e32 v161, 0, v161, vcc
	v_cndmask_b32_e32 v160, 0, v160, vcc
